# C/E residual epilogue: per-row-group vmcnt waits raised to the exact number of younger stores/atomics/prefetches so a group waits only for its own residual loads
# speedup vs baseline: 1.0195x; 1.0087x over previous
.LBB0_240:
	v_or_b32_e32 v106, 48, v194
	v_ashrrev_i32_e32 v107, 31, v106
	s_waitcnt lgkmcnt(0)
	v_lshlrev_b64 v[96:97], 11, v[106:107]
	v_lshl_add_u64 v[96:97], s[54:55], 0, v[96:97]
	v_lshl_add_u64 v[104:105], v[196:197], 1, v[96:97]
	global_load_dwordx4 v[100:103], v[104:105], off
	global_load_dwordx4 v[96:99], v[104:105], off offset:256
	v_lshlrev_b64 v[108:109], 10, v[122:123]
	s_waitcnt vmcnt(6)
	v_lshlrev_b32_e32 v110, 16, v116
	v_and_b32_e32 v111, 0xffff0000, v116
	v_lshlrev_b32_e32 v116, 16, v117
	v_and_b32_e32 v117, 0xffff0000, v117
	v_lshl_add_u64 v[108:109], v[108:109], 0, v[196:197]
	v_pk_add_f32 v[94:95], v[94:95], v[116:117]
	v_pk_add_f32 v[92:93], v[92:93], v[110:111]
	v_lshlrev_b32_e32 v110, 16, v118
	v_and_b32_e32 v111, 0xffff0000, v118
	v_lshlrev_b32_e32 v116, 16, v119
	v_and_b32_e32 v117, 0xffff0000, v119
	v_pk_add_f32 v[90:91], v[90:91], v[116:117]
	v_pk_add_f32 v[88:89], v[88:89], v[110:111]
	s_mov_b64 s[78:79], -1
	s_and_b64 vcc, exec, s[42:43]
	v_lshl_add_u64 v[108:109], v[108:109], 2, s[94:95]
	s_cbranch_vccnz .LBB0_242
	s_mov_b64 s[78:79], 0
	global_store_dwordx4 v[108:109], v[92:95], off
	global_store_dwordx4 v[108:109], v[88:91], off offset:16

.LBB0_244:
	s_waitcnt vmcnt(6)
	v_lshlrev_b32_e32 v88, 16, v112
	v_and_b32_e32 v89, 0xffff0000, v112
	v_lshlrev_b32_e32 v90, 16, v113
	v_and_b32_e32 v91, 0xffff0000, v113
	v_pk_add_f32 v[86:87], v[86:87], v[90:91]
	v_pk_add_f32 v[84:85], v[84:85], v[88:89]
	v_lshlrev_b32_e32 v88, 16, v114
	v_and_b32_e32 v89, 0xffff0000, v114
	v_lshlrev_b32_e32 v90, 16, v115
	v_and_b32_e32 v91, 0xffff0000, v115
	v_pk_add_f32 v[82:83], v[82:83], v[90:91]
	v_pk_add_f32 v[80:81], v[80:81], v[88:89]
	s_and_b64 vcc, exec, s[42:43]
	s_mov_b64 s[78:79], -1
	s_cbranch_vccnz .LBB0_247
	global_store_dwordx4 v[108:109], v[84:87], off offset:512
	global_store_dwordx4 v[108:109], v[80:83], off offset:528
	s_cbranch_execz .LBB0_248

.LBB0_252:
	v_add_u32_e32 v88, 0x80, v194
	v_ashrrev_i32_e32 v89, 31, v88
	s_waitcnt lgkmcnt(0)
	v_lshlrev_b64 v[80:81], 11, v[88:89]
	v_lshl_add_u64 v[80:81], s[54:55], 0, v[80:81]
	v_lshl_add_u64 v[90:91], v[196:197], 1, v[80:81]
	global_load_dwordx4 v[84:87], v[90:91], off
	global_load_dwordx4 v[80:83], v[90:91], off offset:256
	v_lshlrev_b64 v[92:93], 10, v[106:107]
	s_waitcnt vmcnt(6)
	v_lshlrev_b32_e32 v94, 16, v100
	v_and_b32_e32 v95, 0xffff0000, v100
	v_lshlrev_b32_e32 v100, 16, v101
	v_and_b32_e32 v101, 0xffff0000, v101
	v_lshl_add_u64 v[92:93], v[92:93], 0, v[196:197]
	v_pk_add_f32 v[78:79], v[78:79], v[100:101]
	v_pk_add_f32 v[76:77], v[76:77], v[94:95]
	v_lshlrev_b32_e32 v94, 16, v102
	v_and_b32_e32 v95, 0xffff0000, v102
	v_lshlrev_b32_e32 v100, 16, v103
	v_and_b32_e32 v101, 0xffff0000, v103
	v_pk_add_f32 v[74:75], v[74:75], v[100:101]
	v_pk_add_f32 v[72:73], v[72:73], v[94:95]
	s_mov_b64 s[78:79], -1
	s_and_b64 vcc, exec, s[42:43]
	v_lshl_add_u64 v[92:93], v[92:93], 2, s[94:95]
	s_cbranch_vccnz .LBB0_254
	s_mov_b64 s[78:79], 0
	global_store_dwordx4 v[92:93], v[76:79], off
	global_store_dwordx4 v[92:93], v[72:75], off offset:16

.LBB0_256:
	s_waitcnt vmcnt(6)
	v_lshlrev_b32_e32 v72, 16, v96
	v_and_b32_e32 v73, 0xffff0000, v96
	v_lshlrev_b32_e32 v74, 16, v97
	v_and_b32_e32 v75, 0xffff0000, v97
	v_pk_add_f32 v[70:71], v[70:71], v[74:75]
	v_pk_add_f32 v[68:69], v[68:69], v[72:73]
	v_lshlrev_b32_e32 v72, 16, v98
	v_and_b32_e32 v73, 0xffff0000, v98
	v_lshlrev_b32_e32 v74, 16, v99
	v_and_b32_e32 v75, 0xffff0000, v99
	v_pk_add_f32 v[66:67], v[66:67], v[74:75]
	v_pk_add_f32 v[64:65], v[64:65], v[72:73]
	s_and_b64 vcc, exec, s[42:43]
	s_mov_b64 s[78:79], -1
	s_cbranch_vccnz .LBB0_259
	global_store_dwordx4 v[92:93], v[68:71], off offset:512
	global_store_dwordx4 v[92:93], v[64:67], off offset:528
	s_cbranch_execz .LBB0_260

.LBB0_264:
	v_or_b32_e32 v74, 16, v88
	v_ashrrev_i32_e32 v75, 31, v74
	s_waitcnt lgkmcnt(0)
	v_lshlrev_b64 v[64:65], 11, v[74:75]
	v_lshl_add_u64 v[64:65], s[54:55], 0, v[64:65]
	v_lshl_add_u64 v[72:73], v[196:197], 1, v[64:65]
	global_load_dwordx4 v[68:71], v[72:73], off
	global_load_dwordx4 v[64:67], v[72:73], off offset:256
	v_lshlrev_b64 v[76:77], 10, v[88:89]
	s_waitcnt vmcnt(6)
	v_lshlrev_b32_e32 v78, 16, v84
	v_and_b32_e32 v79, 0xffff0000, v84
	v_lshlrev_b32_e32 v84, 16, v85
	v_and_b32_e32 v85, 0xffff0000, v85
	v_lshl_add_u64 v[76:77], v[76:77], 0, v[196:197]
	v_pk_add_f32 v[62:63], v[62:63], v[84:85]
	v_pk_add_f32 v[60:61], v[60:61], v[78:79]
	v_lshlrev_b32_e32 v78, 16, v86
	v_and_b32_e32 v79, 0xffff0000, v86
	v_lshlrev_b32_e32 v84, 16, v87
	v_and_b32_e32 v85, 0xffff0000, v87
	v_pk_add_f32 v[58:59], v[58:59], v[84:85]
	v_pk_add_f32 v[56:57], v[56:57], v[78:79]
	s_mov_b64 s[78:79], -1
	s_and_b64 vcc, exec, s[42:43]
	v_lshl_add_u64 v[76:77], v[76:77], 2, s[94:95]
	s_cbranch_vccnz .LBB0_266
	s_mov_b64 s[78:79], 0
	global_store_dwordx4 v[76:77], v[60:63], off
	global_store_dwordx4 v[76:77], v[56:59], off offset:16

.LBB0_268:
	s_waitcnt vmcnt(6)
	v_lshlrev_b32_e32 v56, 16, v80
	v_and_b32_e32 v57, 0xffff0000, v80
	v_lshlrev_b32_e32 v58, 16, v81
	v_and_b32_e32 v59, 0xffff0000, v81
	v_pk_add_f32 v[54:55], v[54:55], v[58:59]
	v_pk_add_f32 v[52:53], v[52:53], v[56:57]
	v_lshlrev_b32_e32 v56, 16, v82
	v_and_b32_e32 v57, 0xffff0000, v82
	v_lshlrev_b32_e32 v58, 16, v83
	v_and_b32_e32 v59, 0xffff0000, v83
	v_pk_add_f32 v[50:51], v[50:51], v[58:59]
	v_pk_add_f32 v[48:49], v[48:49], v[56:57]
	s_and_b64 vcc, exec, s[42:43]
	s_mov_b64 s[78:79], -1
	s_cbranch_vccnz .LBB0_271
	global_store_dwordx4 v[76:77], v[52:55], off offset:512
	global_store_dwordx4 v[76:77], v[48:51], off offset:528
	s_cbranch_execz .LBB0_272

.LBB0_276:
	v_or_b32_e32 v58, 32, v88
	v_ashrrev_i32_e32 v59, 31, v58
	s_waitcnt lgkmcnt(0)
	v_lshlrev_b64 v[48:49], 11, v[58:59]
	v_lshl_add_u64 v[48:49], s[54:55], 0, v[48:49]
	v_lshl_add_u64 v[56:57], v[196:197], 1, v[48:49]
	global_load_dwordx4 v[52:55], v[56:57], off
	global_load_dwordx4 v[48:51], v[56:57], off offset:256
	v_lshlrev_b64 v[60:61], 10, v[74:75]
	s_waitcnt vmcnt(6)
	v_lshlrev_b32_e32 v62, 16, v68
	v_and_b32_e32 v63, 0xffff0000, v68
	v_lshlrev_b32_e32 v68, 16, v69
	v_and_b32_e32 v69, 0xffff0000, v69
	v_lshl_add_u64 v[60:61], v[60:61], 0, v[196:197]
	v_pk_add_f32 v[46:47], v[46:47], v[68:69]
	v_pk_add_f32 v[44:45], v[44:45], v[62:63]
	v_lshlrev_b32_e32 v62, 16, v70
	v_and_b32_e32 v63, 0xffff0000, v70
	v_lshlrev_b32_e32 v68, 16, v71
	v_and_b32_e32 v69, 0xffff0000, v71
	v_pk_add_f32 v[42:43], v[42:43], v[68:69]
	v_pk_add_f32 v[40:41], v[40:41], v[62:63]
	s_mov_b64 s[78:79], -1
	s_and_b64 vcc, exec, s[42:43]
	v_lshl_add_u64 v[60:61], v[60:61], 2, s[94:95]
	s_cbranch_vccnz .LBB0_278
	s_mov_b64 s[78:79], 0
	global_store_dwordx4 v[60:61], v[44:47], off
	global_store_dwordx4 v[60:61], v[40:43], off offset:16

.LBB0_280:
	s_waitcnt vmcnt(6)
	v_lshlrev_b32_e32 v40, 16, v64
	v_and_b32_e32 v41, 0xffff0000, v64
	v_lshlrev_b32_e32 v42, 16, v65
	v_and_b32_e32 v43, 0xffff0000, v65
	v_pk_add_f32 v[38:39], v[38:39], v[42:43]
	v_pk_add_f32 v[36:37], v[36:37], v[40:41]
	v_lshlrev_b32_e32 v40, 16, v66
	v_and_b32_e32 v41, 0xffff0000, v66
	v_lshlrev_b32_e32 v42, 16, v67
	v_and_b32_e32 v43, 0xffff0000, v67
	v_pk_add_f32 v[34:35], v[34:35], v[42:43]
	v_pk_add_f32 v[32:33], v[32:33], v[40:41]
	s_and_b64 vcc, exec, s[42:43]
	s_mov_b64 s[78:79], -1
	s_cbranch_vccnz .LBB0_283
	global_store_dwordx4 v[60:61], v[36:39], off offset:512
	global_store_dwordx4 v[60:61], v[32:35], off offset:528
	s_cbranch_execz .LBB0_284

.LBB0_288:
	v_or_b32_e32 v42, 48, v88
	v_ashrrev_i32_e32 v43, 31, v42
	s_waitcnt lgkmcnt(0)
	v_lshlrev_b64 v[32:33], 11, v[42:43]
	v_lshl_add_u64 v[32:33], s[54:55], 0, v[32:33]
	v_lshl_add_u64 v[40:41], v[196:197], 1, v[32:33]
	global_load_dwordx4 v[36:39], v[40:41], off
	global_load_dwordx4 v[32:35], v[40:41], off offset:256
	v_lshlrev_b64 v[44:45], 10, v[58:59]
	s_waitcnt vmcnt(6)
	v_lshlrev_b32_e32 v46, 16, v52
	v_and_b32_e32 v47, 0xffff0000, v52
	v_lshlrev_b32_e32 v52, 16, v53
	v_and_b32_e32 v53, 0xffff0000, v53
	v_lshl_add_u64 v[44:45], v[44:45], 0, v[196:197]
	v_pk_add_f32 v[30:31], v[30:31], v[52:53]
	v_pk_add_f32 v[28:29], v[28:29], v[46:47]
	v_lshlrev_b32_e32 v46, 16, v54
	v_and_b32_e32 v47, 0xffff0000, v54
	v_lshlrev_b32_e32 v52, 16, v55
	v_and_b32_e32 v53, 0xffff0000, v55
	v_pk_add_f32 v[26:27], v[26:27], v[52:53]
	v_pk_add_f32 v[24:25], v[24:25], v[46:47]
	s_mov_b64 s[78:79], -1
	s_and_b64 vcc, exec, s[42:43]
	v_lshl_add_u64 v[44:45], v[44:45], 2, s[94:95]
	s_cbranch_vccnz .LBB0_290
	s_mov_b64 s[78:79], 0
	global_store_dwordx4 v[44:45], v[28:31], off
	global_store_dwordx4 v[44:45], v[24:27], off offset:16

.LBB0_292:
	s_waitcnt vmcnt(6)
	v_lshlrev_b32_e32 v24, 16, v48
	v_and_b32_e32 v25, 0xffff0000, v48
	v_lshlrev_b32_e32 v26, 16, v49
	v_and_b32_e32 v27, 0xffff0000, v49
	v_pk_add_f32 v[22:23], v[22:23], v[26:27]
	v_pk_add_f32 v[20:21], v[20:21], v[24:25]
	v_lshlrev_b32_e32 v24, 16, v50
	v_and_b32_e32 v25, 0xffff0000, v50
	v_lshlrev_b32_e32 v26, 16, v51
	v_and_b32_e32 v27, 0xffff0000, v51
	v_pk_add_f32 v[18:19], v[18:19], v[26:27]
	v_pk_add_f32 v[16:17], v[16:17], v[24:25]
	s_and_b64 vcc, exec, s[42:43]
	s_mov_b64 s[78:79], -1
	s_cbranch_vccnz .LBB0_295
	global_store_dwordx4 v[44:45], v[20:23], off offset:512
	global_store_dwordx4 v[44:45], v[16:19], off offset:528
	s_cbranch_execz .LBB0_296

.LBB0_300:
	s_waitcnt lgkmcnt(0)
	v_lshlrev_b64 v[16:17], 10, v[42:43]
	s_waitcnt vmcnt(4)
	v_lshlrev_b32_e32 v18, 16, v36
	v_and_b32_e32 v19, 0xffff0000, v36
	v_lshlrev_b32_e32 v20, 16, v37
	v_and_b32_e32 v21, 0xffff0000, v37
	v_lshl_add_u64 v[16:17], v[16:17], 0, v[196:197]
	v_pk_add_f32 v[14:15], v[14:15], v[20:21]
	v_pk_add_f32 v[12:13], v[12:13], v[18:19]
	v_lshlrev_b32_e32 v18, 16, v38
	v_and_b32_e32 v19, 0xffff0000, v38
	v_lshlrev_b32_e32 v20, 16, v39
	v_and_b32_e32 v21, 0xffff0000, v39
	v_pk_add_f32 v[10:11], v[10:11], v[20:21]
	v_pk_add_f32 v[8:9], v[8:9], v[18:19]
	s_mov_b64 s[78:79], -1
	s_and_b64 vcc, exec, s[42:43]
	v_lshl_add_u64 v[16:17], v[16:17], 2, s[94:95]
	s_cbranch_vccnz .LBB0_302
	s_mov_b64 s[78:79], 0
	global_store_dwordx4 v[16:17], v[12:15], off
	global_store_dwordx4 v[16:17], v[8:11], off offset:16

.LBB0_304:
	s_waitcnt vmcnt(4)
	v_lshlrev_b32_e32 v8, 16, v32
	v_and_b32_e32 v9, 0xffff0000, v32
	v_lshlrev_b32_e32 v10, 16, v33
	v_and_b32_e32 v11, 0xffff0000, v33
	v_pk_add_f32 v[6:7], v[6:7], v[10:11]
	v_pk_add_f32 v[4:5], v[4:5], v[8:9]
	v_lshlrev_b32_e32 v8, 16, v34
	v_and_b32_e32 v9, 0xffff0000, v34
	v_lshlrev_b32_e32 v10, 16, v35
	v_and_b32_e32 v11, 0xffff0000, v35
	v_pk_add_f32 v[2:3], v[2:3], v[10:11]
	v_pk_add_f32 v[0:1], v[0:1], v[8:9]
	s_and_b64 vcc, exec, s[42:43]
	s_mov_b64 s[42:43], -1
	s_cbranch_vccnz .LBB0_307
	global_store_dwordx4 v[16:17], v[4:7], off offset:512
	global_store_dwordx4 v[16:17], v[0:3], off offset:528
	s_cbranch_execz .LBB0_308
